# norm_mod0: modulation slice loads batched 16 at a time (4 round trips instead of 16)
# speedup vs baseline: 1.0203x; 1.0013x over previous
.LBB0_101:
	s_waitcnt vmcnt(4)
	v_min_i32_e32 v24, v144, v177
	v_add_u32_e32 v26, 0xffffe000, v24
	v_ashrrev_i32_e32 v25, 31, v24
	v_cmp_gt_i32_e32 vcc, s12, v24
	v_mov_b32_e32 v28, s39
	v_mov_b32_e32 v29, s37
	v_cndmask_b32_e32 v25, 0, v25, vcc
	v_cndmask_b32_e32 v24, v26, v24, vcc
	v_mov_b32_e32 v30, s38
	v_mov_b32_e32 v31, s36
	v_cndmask_b32_e32 v27, v28, v29, vcc
	v_cndmask_b32_e32 v26, v30, v31, vcc
	v_lshlrev_b64 v[24:25], 12, v[24:25]
	v_lshl_add_u64 v[24:25], v[26:27], 0, v[24:25]
	v_lshl_add_u64 v[24:25], v[24:25], 0, v[146:147]
	v_add_u32_e32 v170, 1, v144
	global_load_dwordx4 v[140:143], v[24:25], off nt
	global_load_dwordx4 v[136:139], v[24:25], off offset:1024 nt
	global_load_dwordx4 v[132:135], v[24:25], off offset:2048 nt
	global_load_dwordx4 v[128:131], v[24:25], off offset:3072 nt
	v_min_i32_e32 v24, v170, v177
	v_ashrrev_i32_e32 v25, 31, v24
	v_add_u32_e32 v26, 0xffffe000, v24
	v_cmp_gt_i32_e32 vcc, s12, v24
	v_add_u32_e32 v168, 2, v144
	v_add_u32_e32 v166, 3, v144
	v_cndmask_b32_e32 v25, 0, v25, vcc
	v_cndmask_b32_e32 v24, v26, v24, vcc
	v_cndmask_b32_e32 v27, v28, v29, vcc
	v_cndmask_b32_e32 v26, v30, v31, vcc
	v_lshlrev_b64 v[24:25], 12, v[24:25]
	v_lshl_add_u64 v[24:25], v[26:27], 0, v[24:25]
	v_lshl_add_u64 v[24:25], v[24:25], 0, v[146:147]
	global_load_dwordx4 v[124:127], v[24:25], off nt
	global_load_dwordx4 v[120:123], v[24:25], off offset:1024 nt
	global_load_dwordx4 v[116:119], v[24:25], off offset:2048 nt
	global_load_dwordx4 v[112:115], v[24:25], off offset:3072 nt
	v_min_i32_e32 v24, v168, v177
	v_ashrrev_i32_e32 v25, 31, v24
	v_add_u32_e32 v26, 0xffffe000, v24
	v_cmp_gt_i32_e32 vcc, s12, v24
	v_add_u32_e32 v164, 4, v144
	v_add_u32_e32 v162, 5, v144
	v_cndmask_b32_e32 v25, 0, v25, vcc
	v_cndmask_b32_e32 v24, v26, v24, vcc
	v_cndmask_b32_e32 v27, v28, v29, vcc
	v_cndmask_b32_e32 v26, v30, v31, vcc
	v_lshlrev_b64 v[24:25], 12, v[24:25]
	v_lshl_add_u64 v[24:25], v[26:27], 0, v[24:25]
	v_lshl_add_u64 v[24:25], v[24:25], 0, v[146:147]
	global_load_dwordx4 v[108:111], v[24:25], off nt
	global_load_dwordx4 v[104:107], v[24:25], off offset:1024 nt
	global_load_dwordx4 v[100:103], v[24:25], off offset:2048 nt
	global_load_dwordx4 v[96:99], v[24:25], off offset:3072 nt
	v_min_i32_e32 v24, v166, v177
	v_ashrrev_i32_e32 v25, 31, v24
	v_add_u32_e32 v26, 0xffffe000, v24
	v_cmp_gt_i32_e32 vcc, s12, v24
	v_add_u32_e32 v145, 0xffffe000, v144
	v_ashrrev_i32_e32 v145, 10, v145
	v_cndmask_b32_e32 v25, 0, v25, vcc
	v_cndmask_b32_e32 v24, v26, v24, vcc
	v_cndmask_b32_e32 v27, v28, v29, vcc
	v_cndmask_b32_e32 v26, v30, v31, vcc
	v_lshlrev_b64 v[24:25], 12, v[24:25]
	v_lshl_add_u64 v[24:25], v[26:27], 0, v[24:25]
	v_lshl_add_u64 v[24:25], v[24:25], 0, v[146:147]
	global_load_dwordx4 v[84:87], v[24:25], off nt
	global_load_dwordx4 v[80:83], v[24:25], off offset:1024 nt
	global_load_dwordx4 v[76:79], v[24:25], off offset:2048 nt
	global_load_dwordx4 v[72:75], v[24:25], off offset:3072 nt
	v_min_i32_e32 v24, v164, v177
	v_ashrrev_i32_e32 v25, 31, v24
	v_add_u32_e32 v26, 0xffffe000, v24
	v_cmp_gt_i32_e32 vcc, s12, v24
	v_add_u32_e32 v145, 1, v145
	s_nop 0
	v_cndmask_b32_e32 v25, 0, v25, vcc
	v_cndmask_b32_e32 v24, v26, v24, vcc
	v_cndmask_b32_e32 v27, v28, v29, vcc
	v_cndmask_b32_e32 v26, v30, v31, vcc
	v_lshlrev_b64 v[24:25], 12, v[24:25]
	v_lshl_add_u64 v[24:25], v[26:27], 0, v[24:25]
	v_min_i32_e32 v26, v162, v177
	v_ashrrev_i32_e32 v27, 31, v26
	v_add_u32_e32 v32, 0xffffe000, v26
	v_cmp_gt_i32_e32 vcc, s12, v26
	v_lshl_add_u64 v[24:25], v[24:25], 0, v[146:147]
	s_nop 0
	v_cndmask_b32_e32 v27, 0, v27, vcc
	v_cndmask_b32_e32 v26, v32, v26, vcc
	v_cndmask_b32_e32 v29, v28, v29, vcc
	v_cndmask_b32_e32 v28, v30, v31, vcc
	v_lshlrev_b64 v[26:27], 12, v[26:27]
	v_lshl_add_u64 v[26:27], v[28:29], 0, v[26:27]
	v_lshl_add_u64 v[26:27], v[26:27], 0, v[146:147]
	global_load_dwordx4 v[60:63], v[24:25], off nt
	global_load_dwordx4 v[56:59], v[24:25], off offset:1024 nt
	global_load_dwordx4 v[52:55], v[24:25], off offset:2048 nt
	global_load_dwordx4 v[48:51], v[24:25], off offset:3072 nt
	global_load_dwordx4 v[36:39], v[26:27], off nt
	global_load_dwordx4 v[32:35], v[26:27], off offset:1024 nt
	global_load_dwordx4 v[28:31], v[26:27], off offset:2048 nt
	s_nop 0
	global_load_dwordx4 v[24:27], v[26:27], off offset:3072 nt
	v_cmp_lt_i32_e32 vcc, s13, v144
	s_nop 1
	v_cndmask_b32_e32 v145, 0, v145, vcc
	v_cmp_ne_u32_e32 vcc, v145, v185
	s_and_saveexec_b64 s[6:7], vcc
	s_cbranch_execz .LBB0_111
	v_mad_i64_i32 v[172:173], s[8:9], v145, s3, v[160:161]
	global_load_dwordx4 v[16:19], v[150:151], off
	global_load_dwordx4 v[20:23], v[152:153], off
	v_add_co_u32_e32 v222, vcc, 0x1410000, v172
	s_nop 1
	v_addc_co_u32_e32 v223, vcc, 0, v173, vcc
	global_load_dwordx4 v[186:189], v[222:223], off
	v_add_co_u32_e32 v222, vcc, 0x1000, v222
	s_nop 1
	v_addc_co_u32_e32 v223, vcc, 0, v223, vcc
	global_load_dwordx4 v[190:193], v[222:223], off
	v_add_co_u32_e32 v222, vcc, 0x1d000, v222
	s_nop 1
	v_addc_co_u32_e32 v223, vcc, 0, v223, vcc
	global_load_dwordx4 v[194:197], v[222:223], off
	v_add_co_u32_e32 v222, vcc, 0x1000, v222
	s_nop 1
	v_addc_co_u32_e32 v223, vcc, 0, v223, vcc
	global_load_dwordx4 v[198:201], v[222:223], off
	v_add_co_u32_e32 v222, vcc, 0x1d000, v222
	s_nop 1
	v_addc_co_u32_e32 v223, vcc, 0, v223, vcc
	global_load_dwordx4 v[202:205], v[222:223], off
	v_add_co_u32_e32 v222, vcc, 0x1000, v222
	s_nop 1
	v_addc_co_u32_e32 v223, vcc, 0, v223, vcc
	global_load_dwordx4 v[206:209], v[222:223], off
	v_add_co_u32_e32 v222, vcc, 0x1d000, v222
	s_nop 1
	v_addc_co_u32_e32 v223, vcc, 0, v223, vcc
	global_load_dwordx4 v[210:213], v[222:223], off
	v_add_co_u32_e32 v222, vcc, 0x1000, v222
	s_nop 1
	v_addc_co_u32_e32 v223, vcc, 0, v223, vcc
	global_load_dwordx4 v[214:217], v[222:223], off
	v_add_co_u32_e32 v222, vcc, 0x1d000, v222
	s_nop 1
	v_addc_co_u32_e32 v223, vcc, 0, v223, vcc
	global_load_dwordx4 v[218:221], v[222:223], off
	v_add_co_u32_e32 v222, vcc, 0x1000, v222
	s_nop 1
	v_addc_co_u32_e32 v223, vcc, 0, v223, vcc
	global_load_dwordx4 v[226:229], v[222:223], off
	v_add_co_u32_e32 v222, vcc, 0x1d000, v222
	s_nop 1
	v_addc_co_u32_e32 v223, vcc, 0, v223, vcc
	global_load_dwordx4 v[230:233], v[222:223], off
	v_add_co_u32_e32 v222, vcc, 0x1000, v222
	s_nop 1
	v_addc_co_u32_e32 v223, vcc, 0, v223, vcc
	global_load_dwordx4 v[234:237], v[222:223], off
	v_add_co_u32_e32 v222, vcc, 0x1d000, v222
	s_nop 1
	v_addc_co_u32_e32 v223, vcc, 0, v223, vcc
	global_load_dwordx4 v[238:241], v[222:223], off
	v_add_co_u32_e32 v222, vcc, 0x1000, v222
	s_nop 1
	v_addc_co_u32_e32 v223, vcc, 0, v223, vcc
	global_load_dwordx4 v[242:245], v[222:223], off
	v_add_co_u32_e32 v222, vcc, 0x1d000, v222
	s_nop 1
	v_addc_co_u32_e32 v223, vcc, 0, v223, vcc
	global_load_dwordx4 v[246:249], v[222:223], off
	v_add_co_u32_e32 v222, vcc, 0x1000, v222
	s_nop 1
	v_addc_co_u32_e32 v223, vcc, 0, v223, vcc
	global_load_dwordx4 v[250:253], v[222:223], off
	s_waitcnt vmcnt(15)
	v_pk_add_f32 v[18:19], v[18:19], v[188:189]
	v_pk_add_f32 v[16:17], v[16:17], v[186:187]
	s_waitcnt vmcnt(14)
	v_pk_add_f32 v[22:23], v[22:23], v[192:193]
	v_pk_add_f32 v[20:21], v[20:21], v[190:191]
	s_waitcnt vmcnt(13)
	v_pk_add_f32 v[18:19], v[18:19], v[196:197]
	v_pk_add_f32 v[16:17], v[16:17], v[194:195]
	s_waitcnt vmcnt(12)
	v_pk_add_f32 v[22:23], v[22:23], v[200:201]
	v_pk_add_f32 v[20:21], v[20:21], v[198:199]
	s_waitcnt vmcnt(11)
	v_pk_add_f32 v[18:19], v[18:19], v[204:205]
	v_pk_add_f32 v[16:17], v[16:17], v[202:203]
	s_waitcnt vmcnt(10)
	v_pk_add_f32 v[22:23], v[22:23], v[208:209]
	v_pk_add_f32 v[20:21], v[20:21], v[206:207]
	s_waitcnt vmcnt(9)
	v_pk_add_f32 v[18:19], v[18:19], v[212:213]
	v_pk_add_f32 v[16:17], v[16:17], v[210:211]
	s_waitcnt vmcnt(8)
	v_pk_add_f32 v[22:23], v[22:23], v[216:217]
	v_pk_add_f32 v[20:21], v[20:21], v[214:215]
	s_waitcnt vmcnt(7)
	v_pk_add_f32 v[18:19], v[18:19], v[220:221]
	v_pk_add_f32 v[16:17], v[16:17], v[218:219]
	s_waitcnt vmcnt(6)
	v_pk_add_f32 v[22:23], v[22:23], v[228:229]
	v_pk_add_f32 v[20:21], v[20:21], v[226:227]
	s_waitcnt vmcnt(5)
	v_pk_add_f32 v[18:19], v[18:19], v[232:233]
	v_pk_add_f32 v[16:17], v[16:17], v[230:231]
	s_waitcnt vmcnt(4)
	v_pk_add_f32 v[22:23], v[22:23], v[236:237]
	v_pk_add_f32 v[20:21], v[20:21], v[234:235]
	s_waitcnt vmcnt(3)
	v_pk_add_f32 v[18:19], v[18:19], v[240:241]
	v_pk_add_f32 v[16:17], v[16:17], v[238:239]
	s_waitcnt vmcnt(2)
	v_pk_add_f32 v[22:23], v[22:23], v[244:245]
	v_pk_add_f32 v[20:21], v[20:21], v[242:243]
	s_waitcnt vmcnt(1)
	v_pk_add_f32 v[18:19], v[18:19], v[248:249]
	v_pk_add_f32 v[16:17], v[16:17], v[246:247]
	s_waitcnt vmcnt(0)
	v_pk_add_f32 v[22:23], v[22:23], v[252:253]
	v_pk_add_f32 v[20:21], v[20:21], v[250:251]
	global_load_dwordx4 v[40:43], v[150:151], off offset:1024
	global_load_dwordx4 v[44:47], v[154:155], off
	v_add_co_u32_e32 v222, vcc, 0x1410000, v172
	s_nop 1
	v_addc_co_u32_e32 v223, vcc, 0, v173, vcc
	global_load_dwordx4 v[186:189], v[222:223], off offset:1024
	v_add_co_u32_e32 v222, vcc, 0x1000, v222
	s_nop 1
	v_addc_co_u32_e32 v223, vcc, 0, v223, vcc
	global_load_dwordx4 v[190:193], v[222:223], off offset:1024
	v_add_co_u32_e32 v222, vcc, 0x1d000, v222
	s_nop 1
	v_addc_co_u32_e32 v223, vcc, 0, v223, vcc
	global_load_dwordx4 v[194:197], v[222:223], off offset:1024
	v_add_co_u32_e32 v222, vcc, 0x1000, v222
	s_nop 1
	v_addc_co_u32_e32 v223, vcc, 0, v223, vcc
	global_load_dwordx4 v[198:201], v[222:223], off offset:1024
	v_add_co_u32_e32 v222, vcc, 0x1d000, v222
	s_nop 1
	v_addc_co_u32_e32 v223, vcc, 0, v223, vcc
	global_load_dwordx4 v[202:205], v[222:223], off offset:1024
	v_add_co_u32_e32 v222, vcc, 0x1000, v222
	s_nop 1
	v_addc_co_u32_e32 v223, vcc, 0, v223, vcc
	global_load_dwordx4 v[206:209], v[222:223], off offset:1024
	v_add_co_u32_e32 v222, vcc, 0x1d000, v222
	s_nop 1
	v_addc_co_u32_e32 v223, vcc, 0, v223, vcc
	global_load_dwordx4 v[210:213], v[222:223], off offset:1024
	v_add_co_u32_e32 v222, vcc, 0x1000, v222
	s_nop 1
	v_addc_co_u32_e32 v223, vcc, 0, v223, vcc
	global_load_dwordx4 v[214:217], v[222:223], off offset:1024
	v_add_co_u32_e32 v222, vcc, 0x1d000, v222
	s_nop 1
	v_addc_co_u32_e32 v223, vcc, 0, v223, vcc
	global_load_dwordx4 v[218:221], v[222:223], off offset:1024
	v_add_co_u32_e32 v222, vcc, 0x1000, v222
	s_nop 1
	v_addc_co_u32_e32 v223, vcc, 0, v223, vcc
	global_load_dwordx4 v[226:229], v[222:223], off offset:1024
	v_add_co_u32_e32 v222, vcc, 0x1d000, v222
	s_nop 1
	v_addc_co_u32_e32 v223, vcc, 0, v223, vcc
	global_load_dwordx4 v[230:233], v[222:223], off offset:1024
	v_add_co_u32_e32 v222, vcc, 0x1000, v222
	s_nop 1
	v_addc_co_u32_e32 v223, vcc, 0, v223, vcc
	global_load_dwordx4 v[234:237], v[222:223], off offset:1024
	v_add_co_u32_e32 v222, vcc, 0x1d000, v222
	s_nop 1
	v_addc_co_u32_e32 v223, vcc, 0, v223, vcc
	global_load_dwordx4 v[238:241], v[222:223], off offset:1024
	v_add_co_u32_e32 v222, vcc, 0x1000, v222
	s_nop 1
	v_addc_co_u32_e32 v223, vcc, 0, v223, vcc
	global_load_dwordx4 v[242:245], v[222:223], off offset:1024
	v_add_co_u32_e32 v222, vcc, 0x1d000, v222
	s_nop 1
	v_addc_co_u32_e32 v223, vcc, 0, v223, vcc
	global_load_dwordx4 v[246:249], v[222:223], off offset:1024
	v_add_co_u32_e32 v222, vcc, 0x1000, v222
	s_nop 1
	v_addc_co_u32_e32 v223, vcc, 0, v223, vcc
	global_load_dwordx4 v[250:253], v[222:223], off offset:1024
	s_waitcnt vmcnt(15)
	v_pk_add_f32 v[42:43], v[42:43], v[188:189]
	v_pk_add_f32 v[40:41], v[40:41], v[186:187]
	s_waitcnt vmcnt(14)
	v_pk_add_f32 v[46:47], v[46:47], v[192:193]
	v_pk_add_f32 v[44:45], v[44:45], v[190:191]
	s_waitcnt vmcnt(13)
	v_pk_add_f32 v[42:43], v[42:43], v[196:197]
	v_pk_add_f32 v[40:41], v[40:41], v[194:195]
	s_waitcnt vmcnt(12)
	v_pk_add_f32 v[46:47], v[46:47], v[200:201]
	v_pk_add_f32 v[44:45], v[44:45], v[198:199]
	s_waitcnt vmcnt(11)
	v_pk_add_f32 v[42:43], v[42:43], v[204:205]
	v_pk_add_f32 v[40:41], v[40:41], v[202:203]
	s_waitcnt vmcnt(10)
	v_pk_add_f32 v[46:47], v[46:47], v[208:209]
	v_pk_add_f32 v[44:45], v[44:45], v[206:207]
	s_waitcnt vmcnt(9)
	v_pk_add_f32 v[42:43], v[42:43], v[212:213]
	v_pk_add_f32 v[40:41], v[40:41], v[210:211]
	s_waitcnt vmcnt(8)
	v_pk_add_f32 v[46:47], v[46:47], v[216:217]
	v_pk_add_f32 v[44:45], v[44:45], v[214:215]
	s_waitcnt vmcnt(7)
	v_pk_add_f32 v[42:43], v[42:43], v[220:221]
	v_pk_add_f32 v[40:41], v[40:41], v[218:219]
	s_waitcnt vmcnt(6)
	v_pk_add_f32 v[46:47], v[46:47], v[228:229]
	v_pk_add_f32 v[44:45], v[44:45], v[226:227]
	s_waitcnt vmcnt(5)
	v_pk_add_f32 v[42:43], v[42:43], v[232:233]
	v_pk_add_f32 v[40:41], v[40:41], v[230:231]
	s_waitcnt vmcnt(4)
	v_pk_add_f32 v[46:47], v[46:47], v[236:237]
	v_pk_add_f32 v[44:45], v[44:45], v[234:235]
	s_waitcnt vmcnt(3)
	v_pk_add_f32 v[42:43], v[42:43], v[240:241]
	v_pk_add_f32 v[40:41], v[40:41], v[238:239]
	s_waitcnt vmcnt(2)
	v_pk_add_f32 v[46:47], v[46:47], v[244:245]
	v_pk_add_f32 v[44:45], v[44:45], v[242:243]
	s_waitcnt vmcnt(1)
	v_pk_add_f32 v[42:43], v[42:43], v[248:249]
	v_pk_add_f32 v[40:41], v[40:41], v[246:247]
	s_waitcnt vmcnt(0)
	v_pk_add_f32 v[46:47], v[46:47], v[252:253]
	v_pk_add_f32 v[44:45], v[44:45], v[250:251]
	global_load_dwordx4 v[64:67], v[150:151], off offset:2048
	global_load_dwordx4 v[68:71], v[156:157], off
	v_add_co_u32_e32 v222, vcc, 0x1410000, v172
	s_nop 1
	v_addc_co_u32_e32 v223, vcc, 0, v173, vcc
	global_load_dwordx4 v[186:189], v[222:223], off offset:2048
	v_add_co_u32_e32 v222, vcc, 0x1000, v222
	s_nop 1
	v_addc_co_u32_e32 v223, vcc, 0, v223, vcc
	global_load_dwordx4 v[190:193], v[222:223], off offset:2048
	v_add_co_u32_e32 v222, vcc, 0x1d000, v222
	s_nop 1
	v_addc_co_u32_e32 v223, vcc, 0, v223, vcc
	global_load_dwordx4 v[194:197], v[222:223], off offset:2048
	v_add_co_u32_e32 v222, vcc, 0x1000, v222
	s_nop 1
	v_addc_co_u32_e32 v223, vcc, 0, v223, vcc
	global_load_dwordx4 v[198:201], v[222:223], off offset:2048
	v_add_co_u32_e32 v222, vcc, 0x1d000, v222
	s_nop 1
	v_addc_co_u32_e32 v223, vcc, 0, v223, vcc
	global_load_dwordx4 v[202:205], v[222:223], off offset:2048
	v_add_co_u32_e32 v222, vcc, 0x1000, v222
	s_nop 1
	v_addc_co_u32_e32 v223, vcc, 0, v223, vcc
	global_load_dwordx4 v[206:209], v[222:223], off offset:2048
	v_add_co_u32_e32 v222, vcc, 0x1d000, v222
	s_nop 1
	v_addc_co_u32_e32 v223, vcc, 0, v223, vcc
	global_load_dwordx4 v[210:213], v[222:223], off offset:2048
	v_add_co_u32_e32 v222, vcc, 0x1000, v222
	s_nop 1
	v_addc_co_u32_e32 v223, vcc, 0, v223, vcc
	global_load_dwordx4 v[214:217], v[222:223], off offset:2048
	v_add_co_u32_e32 v222, vcc, 0x1d000, v222
	s_nop 1
	v_addc_co_u32_e32 v223, vcc, 0, v223, vcc
	global_load_dwordx4 v[218:221], v[222:223], off offset:2048
	v_add_co_u32_e32 v222, vcc, 0x1000, v222
	s_nop 1
	v_addc_co_u32_e32 v223, vcc, 0, v223, vcc
	global_load_dwordx4 v[226:229], v[222:223], off offset:2048
	v_add_co_u32_e32 v222, vcc, 0x1d000, v222
	s_nop 1
	v_addc_co_u32_e32 v223, vcc, 0, v223, vcc
	global_load_dwordx4 v[230:233], v[222:223], off offset:2048
	v_add_co_u32_e32 v222, vcc, 0x1000, v222
	s_nop 1
	v_addc_co_u32_e32 v223, vcc, 0, v223, vcc
	global_load_dwordx4 v[234:237], v[222:223], off offset:2048
	v_add_co_u32_e32 v222, vcc, 0x1d000, v222
	s_nop 1
	v_addc_co_u32_e32 v223, vcc, 0, v223, vcc
	global_load_dwordx4 v[238:241], v[222:223], off offset:2048
	v_add_co_u32_e32 v222, vcc, 0x1000, v222
	s_nop 1
	v_addc_co_u32_e32 v223, vcc, 0, v223, vcc
	global_load_dwordx4 v[242:245], v[222:223], off offset:2048
	v_add_co_u32_e32 v222, vcc, 0x1d000, v222
	s_nop 1
	v_addc_co_u32_e32 v223, vcc, 0, v223, vcc
	global_load_dwordx4 v[246:249], v[222:223], off offset:2048
	v_add_co_u32_e32 v222, vcc, 0x1000, v222
	s_nop 1
	v_addc_co_u32_e32 v223, vcc, 0, v223, vcc
	global_load_dwordx4 v[250:253], v[222:223], off offset:2048
	s_waitcnt vmcnt(15)
	v_pk_add_f32 v[66:67], v[66:67], v[188:189]
	v_pk_add_f32 v[64:65], v[64:65], v[186:187]
	s_waitcnt vmcnt(14)
	v_pk_add_f32 v[70:71], v[70:71], v[192:193]
	v_pk_add_f32 v[68:69], v[68:69], v[190:191]
	s_waitcnt vmcnt(13)
	v_pk_add_f32 v[66:67], v[66:67], v[196:197]
	v_pk_add_f32 v[64:65], v[64:65], v[194:195]
	s_waitcnt vmcnt(12)
	v_pk_add_f32 v[70:71], v[70:71], v[200:201]
	v_pk_add_f32 v[68:69], v[68:69], v[198:199]
	s_waitcnt vmcnt(11)
	v_pk_add_f32 v[66:67], v[66:67], v[204:205]
	v_pk_add_f32 v[64:65], v[64:65], v[202:203]
	s_waitcnt vmcnt(10)
	v_pk_add_f32 v[70:71], v[70:71], v[208:209]
	v_pk_add_f32 v[68:69], v[68:69], v[206:207]
	s_waitcnt vmcnt(9)
	v_pk_add_f32 v[66:67], v[66:67], v[212:213]
	v_pk_add_f32 v[64:65], v[64:65], v[210:211]
	s_waitcnt vmcnt(8)
	v_pk_add_f32 v[70:71], v[70:71], v[216:217]
	v_pk_add_f32 v[68:69], v[68:69], v[214:215]
	s_waitcnt vmcnt(7)
	v_pk_add_f32 v[66:67], v[66:67], v[220:221]
	v_pk_add_f32 v[64:65], v[64:65], v[218:219]
	s_waitcnt vmcnt(6)
	v_pk_add_f32 v[70:71], v[70:71], v[228:229]
	v_pk_add_f32 v[68:69], v[68:69], v[226:227]
	s_waitcnt vmcnt(5)
	v_pk_add_f32 v[66:67], v[66:67], v[232:233]
	v_pk_add_f32 v[64:65], v[64:65], v[230:231]
	s_waitcnt vmcnt(4)
	v_pk_add_f32 v[70:71], v[70:71], v[236:237]
	v_pk_add_f32 v[68:69], v[68:69], v[234:235]
	s_waitcnt vmcnt(3)
	v_pk_add_f32 v[66:67], v[66:67], v[240:241]
	v_pk_add_f32 v[64:65], v[64:65], v[238:239]
	s_waitcnt vmcnt(2)
	v_pk_add_f32 v[70:71], v[70:71], v[244:245]
	v_pk_add_f32 v[68:69], v[68:69], v[242:243]
	s_waitcnt vmcnt(1)
	v_pk_add_f32 v[66:67], v[66:67], v[248:249]
	v_pk_add_f32 v[64:65], v[64:65], v[246:247]
	s_waitcnt vmcnt(0)
	v_pk_add_f32 v[70:71], v[70:71], v[252:253]
	v_pk_add_f32 v[68:69], v[68:69], v[250:251]
	global_load_dwordx4 v[88:91], v[150:151], off offset:3072
	global_load_dwordx4 v[92:95], v[158:159], off
	v_add_co_u32_e32 v222, vcc, 0x1410000, v172
	s_nop 1
	v_addc_co_u32_e32 v223, vcc, 0, v173, vcc
	global_load_dwordx4 v[186:189], v[222:223], off offset:3072
	v_add_co_u32_e32 v222, vcc, 0x1000, v222
	s_nop 1
	v_addc_co_u32_e32 v223, vcc, 0, v223, vcc
	global_load_dwordx4 v[190:193], v[222:223], off offset:3072
	v_add_co_u32_e32 v222, vcc, 0x1d000, v222
	s_nop 1
	v_addc_co_u32_e32 v223, vcc, 0, v223, vcc
	global_load_dwordx4 v[194:197], v[222:223], off offset:3072
	v_add_co_u32_e32 v222, vcc, 0x1000, v222
	s_nop 1
	v_addc_co_u32_e32 v223, vcc, 0, v223, vcc
	global_load_dwordx4 v[198:201], v[222:223], off offset:3072
	v_add_co_u32_e32 v222, vcc, 0x1d000, v222
	s_nop 1
	v_addc_co_u32_e32 v223, vcc, 0, v223, vcc
	global_load_dwordx4 v[202:205], v[222:223], off offset:3072
	v_add_co_u32_e32 v222, vcc, 0x1000, v222
	s_nop 1
	v_addc_co_u32_e32 v223, vcc, 0, v223, vcc
	global_load_dwordx4 v[206:209], v[222:223], off offset:3072
	v_add_co_u32_e32 v222, vcc, 0x1d000, v222
	s_nop 1
	v_addc_co_u32_e32 v223, vcc, 0, v223, vcc
	global_load_dwordx4 v[210:213], v[222:223], off offset:3072
	v_add_co_u32_e32 v222, vcc, 0x1000, v222
	s_nop 1
	v_addc_co_u32_e32 v223, vcc, 0, v223, vcc
	global_load_dwordx4 v[214:217], v[222:223], off offset:3072
	v_add_co_u32_e32 v222, vcc, 0x1d000, v222
	s_nop 1
	v_addc_co_u32_e32 v223, vcc, 0, v223, vcc
	global_load_dwordx4 v[218:221], v[222:223], off offset:3072
	v_add_co_u32_e32 v222, vcc, 0x1000, v222
	s_nop 1
	v_addc_co_u32_e32 v223, vcc, 0, v223, vcc
	global_load_dwordx4 v[226:229], v[222:223], off offset:3072
	v_add_co_u32_e32 v222, vcc, 0x1d000, v222
	s_nop 1
	v_addc_co_u32_e32 v223, vcc, 0, v223, vcc
	global_load_dwordx4 v[230:233], v[222:223], off offset:3072
	v_add_co_u32_e32 v222, vcc, 0x1000, v222
	s_nop 1
	v_addc_co_u32_e32 v223, vcc, 0, v223, vcc
	global_load_dwordx4 v[234:237], v[222:223], off offset:3072
	v_add_co_u32_e32 v222, vcc, 0x1d000, v222
	s_nop 1
	v_addc_co_u32_e32 v223, vcc, 0, v223, vcc
	global_load_dwordx4 v[238:241], v[222:223], off offset:3072
	v_add_co_u32_e32 v222, vcc, 0x1000, v222
	s_nop 1
	v_addc_co_u32_e32 v223, vcc, 0, v223, vcc
	global_load_dwordx4 v[242:245], v[222:223], off offset:3072
	v_add_co_u32_e32 v222, vcc, 0x1d000, v222
	s_nop 1
	v_addc_co_u32_e32 v223, vcc, 0, v223, vcc
	global_load_dwordx4 v[246:249], v[222:223], off offset:3072
	v_add_co_u32_e32 v222, vcc, 0x1000, v222
	s_nop 1
	v_addc_co_u32_e32 v223, vcc, 0, v223, vcc
	global_load_dwordx4 v[250:253], v[222:223], off offset:3072
	s_waitcnt vmcnt(15)
	v_pk_add_f32 v[90:91], v[90:91], v[188:189]
	v_pk_add_f32 v[88:89], v[88:89], v[186:187]
	s_waitcnt vmcnt(14)
	v_pk_add_f32 v[94:95], v[94:95], v[192:193]
	v_pk_add_f32 v[92:93], v[92:93], v[190:191]
	s_waitcnt vmcnt(13)
	v_pk_add_f32 v[90:91], v[90:91], v[196:197]
	v_pk_add_f32 v[88:89], v[88:89], v[194:195]
	s_waitcnt vmcnt(12)
	v_pk_add_f32 v[94:95], v[94:95], v[200:201]
	v_pk_add_f32 v[92:93], v[92:93], v[198:199]
	s_waitcnt vmcnt(11)
	v_pk_add_f32 v[90:91], v[90:91], v[204:205]
	v_pk_add_f32 v[88:89], v[88:89], v[202:203]
	s_waitcnt vmcnt(10)
	v_pk_add_f32 v[94:95], v[94:95], v[208:209]
	v_pk_add_f32 v[92:93], v[92:93], v[206:207]
	s_waitcnt vmcnt(9)
	v_pk_add_f32 v[90:91], v[90:91], v[212:213]
	v_pk_add_f32 v[88:89], v[88:89], v[210:211]
	s_waitcnt vmcnt(8)
	v_pk_add_f32 v[94:95], v[94:95], v[216:217]
	v_pk_add_f32 v[92:93], v[92:93], v[214:215]
	s_waitcnt vmcnt(7)
	v_pk_add_f32 v[90:91], v[90:91], v[220:221]
	v_pk_add_f32 v[88:89], v[88:89], v[218:219]
	s_waitcnt vmcnt(6)
	v_pk_add_f32 v[94:95], v[94:95], v[228:229]
	v_pk_add_f32 v[92:93], v[92:93], v[226:227]
	s_waitcnt vmcnt(5)
	v_pk_add_f32 v[90:91], v[90:91], v[232:233]
	v_pk_add_f32 v[88:89], v[88:89], v[230:231]
	s_waitcnt vmcnt(4)
	v_pk_add_f32 v[94:95], v[94:95], v[236:237]
	v_pk_add_f32 v[92:93], v[92:93], v[234:235]
	s_waitcnt vmcnt(3)
	v_pk_add_f32 v[90:91], v[90:91], v[240:241]
	v_pk_add_f32 v[88:89], v[88:89], v[238:239]
	s_waitcnt vmcnt(2)
	v_pk_add_f32 v[94:95], v[94:95], v[244:245]
	v_pk_add_f32 v[92:93], v[92:93], v[242:243]
	s_waitcnt vmcnt(1)
	v_pk_add_f32 v[90:91], v[90:91], v[248:249]
	v_pk_add_f32 v[88:89], v[88:89], v[246:247]
	s_waitcnt vmcnt(0)
	v_pk_add_f32 v[94:95], v[94:95], v[252:253]
	v_pk_add_f32 v[92:93], v[92:93], v[250:251]
	v_mov_b32_e32 v185, v145
